# row-statistic and attention row-max cross-lane reductions by permlane16/32 swaps instead of ds_bpermute
# baseline (speedup 1.0000x reference)
.LBB0_189:
	v_readlane_b32 s34, v255, 11
	v_readlane_b32 s35, v255, 12
	v_cndmask_b32_e64 v1, v50, v232, s[8:9]
	v_cndmask_b32_e64 v58, v58, v232, s[40:41]
	v_cndmask_b32_e64 v50, v66, v232, s[34:35]
	v_readlane_b32 s34, v255, 13
	v_readlane_b32 s35, v255, 14
	v_cndmask_b32_e64 v50, v50, v66, s[8:9]
	v_cndmask_b32_e64 v59, v59, v232, s[44:45]
	v_cndmask_b32_e64 v51, v51, v232, s[34:35]
	v_readlane_b32 s34, v255, 15
	v_readlane_b32 s35, v255, 16
	v_cndmask_b32_e64 v60, v60, v232, s[48:49]
	v_cndmask_b32_e64 v61, v61, v232, s[52:53]
	v_cndmask_b32_e64 v52, v52, v232, s[34:35]
	v_readlane_b32 s34, v255, 17
	v_readlane_b32 s35, v255, 18
	v_cndmask_b32_e64 v62, v62, v232, s[56:57]
	v_cndmask_b32_e64 v63, v63, v232, s[60:61]
	v_cndmask_b32_e64 v66, v68, v232, s[34:35]
	v_readlane_b32 s34, v255, 19
	v_readlane_b32 s35, v255, 20
	v_cndmask_b32_e64 v64, v64, v232, s[64:65]
	v_cndmask_b32_e64 v65, v65, v232, s[68:69]
	v_cndmask_b32_e64 v53, v53, v232, s[34:35]
	v_readlane_b32 s34, v255, 21
	v_readlane_b32 s35, v255, 22
	v_cndmask_b32_e64 v67, v232, v67, s[8:9]
	s_andn2_b64 vcc, exec, s[74:75]
	v_cndmask_b32_e64 v68, v69, v232, s[34:35]
	v_readlane_b32 s34, v255, 23
	v_readlane_b32 s35, v255, 24
	s_nop 1
	v_cndmask_b32_e64 v54, v54, v232, s[34:35]
	v_readlane_b32 s34, v255, 25
	v_readlane_b32 s35, v255, 26
	s_nop 1
	v_cndmask_b32_e64 v69, v70, v232, s[34:35]
	v_readlane_b32 s34, v255, 27
	v_readlane_b32 s35, v255, 28
	s_nop 1
	v_cndmask_b32_e64 v55, v55, v232, s[34:35]
	v_readlane_b32 s34, v255, 29
	v_readlane_b32 s35, v255, 30
	s_nop 1
	v_cndmask_b32_e64 v70, v71, v232, s[34:35]
	v_readlane_b32 s34, v255, 31
	v_readlane_b32 s35, v255, 32
	s_nop 1
	v_cndmask_b32_e64 v56, v56, v232, s[34:35]
	v_readlane_b32 s34, v255, 33
	v_readlane_b32 s35, v255, 34
	s_nop 1
	v_cndmask_b32_e64 v71, v72, v232, s[34:35]
	v_readlane_b32 s34, v255, 35
	v_readlane_b32 s35, v255, 36
	v_cndmask_b32_e64 v72, v73, v232, s[38:39]
	v_cndmask_b32_e64 v73, v74, v232, s[16:17]
	v_cndmask_b32_e64 v57, v57, v232, s[34:35]
	s_mov_b32 s34, 0xf149f2ca
	v_cndmask_b32_e64 v74, v75, v232, s[46:47]
	v_cndmask_b32_e64 v75, v76, v232, s[50:51]
	v_cndmask_b32_e64 v76, v77, v232, s[54:55]
	v_cndmask_b32_e64 v77, v78, v232, s[58:59]
	v_cndmask_b32_e64 v78, v79, v232, s[62:63]
	v_cndmask_b32_e64 v79, v80, v232, s[66:67]
	v_cndmask_b32_e64 v80, v81, v232, s[70:71]
	v_max3_f32 v81, v1, s34, v51
	v_max3_f32 v81, v81, v52, v53
	v_max3_f32 v81, v81, v54, v55
	v_max3_f32 v81, v81, v56, v57
	v_max3_f32 v81, v81, v58, v59
	v_max3_f32 v81, v81, v60, v61
	v_max3_f32 v81, v81, v62, v63
	v_max3_f32 v81, v81, v64, v65
	v_max3_f32 v81, v81, v2, v3
	v_max3_f32 v81, v81, v4, v5
	v_max3_f32 v81, v81, v6, v7
	v_max3_f32 v81, v81, v8, v9
	v_max3_f32 v81, v81, v10, v11
	v_max3_f32 v81, v81, v12, v13
	v_max3_f32 v81, v81, v14, v15
	v_max3_f32 v81, v81, v16, v17
	v_max3_f32 v81, v81, v34, v35
	v_max3_f32 v81, v81, v36, v37
	v_max3_f32 v81, v81, v38, v39
	v_max3_f32 v81, v81, v40, v41
	v_max3_f32 v81, v81, v42, v43
	v_max3_f32 v81, v81, v44, v45
	v_max3_f32 v81, v81, v46, v47
	v_max3_f32 v81, v81, v48, v49
	v_max3_f32 v81, v81, v18, v19
	v_max3_f32 v81, v81, v20, v21
	v_max3_f32 v81, v81, v22, v23
	v_max3_f32 v81, v81, v24, v25
	v_max3_f32 v81, v81, v26, v27
	v_max3_f32 v81, v81, v28, v29
	v_max3_f32 v81, v81, v30, v31
	v_max3_f32 v81, v81, v32, v33
	v_max3_f32 v81, v81, v50, v67
	v_max3_f32 v81, v81, v66, v68
	v_max3_f32 v81, v81, v69, v70
	v_max3_f32 v81, v81, v71, v72
	v_max3_f32 v81, v81, v73, v74
	v_max3_f32 v81, v81, v75, v76
	v_max3_f32 v81, v81, v77, v78
	v_max3_f32 v81, v81, v79, v80
	v_mov_b32_e32 v225, v81
	s_nop 1
	v_permlane32_swap_b32_e32 v81, v225
	s_waitcnt lgkmcnt(0)
	v_max_f32_e32 v225, v225, v225
	v_max_f32_e32 v81, v81, v225
	v_sub_f32_e32 v1, v1, v81
	v_exp_f32_e32 v1, v1
	v_sub_f32_e32 v51, v51, v81
	v_exp_f32_e32 v51, v51
	v_sub_f32_e32 v52, v52, v81
	v_exp_f32_e32 v52, v52
	v_sub_f32_e32 v53, v53, v81
	v_exp_f32_e32 v53, v53
	v_sub_f32_e32 v54, v54, v81
	v_add_f32_e32 v225, 0, v1
	v_exp_f32_e32 v54, v54
	v_sub_f32_e32 v55, v55, v81
	v_add_f32_e32 v225, v51, v225
	v_exp_f32_e32 v55, v55
	v_sub_f32_e32 v56, v56, v81
	v_add_f32_e32 v225, v52, v225
	v_exp_f32_e32 v56, v56
	v_sub_f32_e32 v57, v57, v81
	v_add_f32_e32 v225, v53, v225
	v_exp_f32_e32 v57, v57
	v_sub_f32_e32 v58, v58, v81
	v_add_f32_e32 v225, v54, v225
	v_exp_f32_e32 v58, v58
	v_sub_f32_e32 v59, v59, v81
	v_add_f32_e32 v225, v55, v225
	v_exp_f32_e32 v59, v59
	v_sub_f32_e32 v60, v60, v81
	v_add_f32_e32 v225, v56, v225
	v_exp_f32_e32 v60, v60
	v_sub_f32_e32 v61, v61, v81
	v_add_f32_e32 v225, v57, v225
	v_exp_f32_e32 v61, v61
	v_sub_f32_e32 v62, v62, v81
	v_add_f32_e32 v225, v58, v225
	v_exp_f32_e32 v62, v62
	v_sub_f32_e32 v63, v63, v81
	v_add_f32_e32 v225, v59, v225
	v_exp_f32_e32 v63, v63
	v_sub_f32_e32 v64, v64, v81
	v_add_f32_e32 v225, v60, v225
	v_exp_f32_e32 v64, v64
	v_sub_f32_e32 v65, v65, v81
	v_add_f32_e32 v225, v61, v225
	v_exp_f32_e32 v65, v65
	v_sub_f32_e32 v2, v2, v81
	v_add_f32_e32 v225, v62, v225
	v_exp_f32_e32 v230, v2
	v_sub_f32_e32 v2, v3, v81
	v_add_f32_e32 v225, v63, v225
	v_exp_f32_e32 v231, v2
	v_sub_f32_e32 v2, v4, v81
	v_add_f32_e32 v225, v64, v225
	v_exp_f32_e32 v237, v2
	v_sub_f32_e32 v2, v5, v81
	v_add_f32_e32 v225, v65, v225
	v_exp_f32_e32 v238, v2
	v_sub_f32_e32 v3, v6, v81
	v_add_f32_e32 v2, v230, v225
	v_exp_f32_e32 v225, v3
	v_sub_f32_e32 v3, v7, v81
	v_add_f32_e32 v2, v231, v2
	v_exp_f32_e32 v239, v3
	v_sub_f32_e32 v3, v8, v81
	v_add_f32_e32 v2, v237, v2
	v_exp_f32_e32 v240, v3
	v_sub_f32_e32 v3, v9, v81
	v_add_f32_e32 v2, v238, v2
	v_exp_f32_e32 v241, v3
	v_sub_f32_e32 v3, v10, v81
	v_add_f32_e32 v2, v225, v2
	v_exp_f32_e32 v10, v3
	v_sub_f32_e32 v3, v11, v81
	v_add_f32_e32 v2, v239, v2
	v_exp_f32_e32 v11, v3
	v_sub_f32_e32 v3, v12, v81
	v_add_f32_e32 v2, v240, v2
	v_exp_f32_e32 v12, v3
	v_sub_f32_e32 v3, v13, v81
	v_add_f32_e32 v2, v241, v2
	v_exp_f32_e32 v13, v3
	v_sub_f32_e32 v3, v14, v81
	v_add_f32_e32 v2, v10, v2
	v_exp_f32_e32 v14, v3
	v_sub_f32_e32 v3, v15, v81
	v_add_f32_e32 v2, v11, v2
	v_exp_f32_e32 v15, v3
	v_sub_f32_e32 v3, v16, v81
	v_add_f32_e32 v2, v12, v2
	v_exp_f32_e32 v16, v3
	v_sub_f32_e32 v3, v17, v81
	v_add_f32_e32 v2, v13, v2
	v_exp_f32_e32 v17, v3
	v_sub_f32_e32 v3, v34, v81
	v_add_f32_e32 v2, v14, v2
	v_exp_f32_e32 v34, v3
	v_sub_f32_e32 v3, v35, v81
	v_add_f32_e32 v2, v15, v2
	v_exp_f32_e32 v35, v3
	v_sub_f32_e32 v3, v36, v81
	v_add_f32_e32 v2, v16, v2
	v_exp_f32_e32 v36, v3
	v_sub_f32_e32 v3, v37, v81
	v_add_f32_e32 v2, v17, v2
	v_exp_f32_e32 v37, v3
	v_sub_f32_e32 v3, v38, v81
	v_add_f32_e32 v2, v34, v2
	v_exp_f32_e32 v38, v3
	v_sub_f32_e32 v3, v39, v81
	v_add_f32_e32 v2, v35, v2
	v_exp_f32_e32 v39, v3
	v_sub_f32_e32 v3, v40, v81
	v_add_f32_e32 v2, v36, v2
	v_exp_f32_e32 v40, v3
	v_sub_f32_e32 v3, v41, v81
	v_add_f32_e32 v2, v37, v2
	v_exp_f32_e32 v41, v3
	v_sub_f32_e32 v3, v42, v81
	v_add_f32_e32 v2, v38, v2
	v_exp_f32_e32 v42, v3
	v_sub_f32_e32 v3, v43, v81
	v_add_f32_e32 v2, v39, v2
	v_exp_f32_e32 v43, v3
	v_sub_f32_e32 v3, v44, v81
	v_add_f32_e32 v2, v40, v2
	v_exp_f32_e32 v44, v3
	v_sub_f32_e32 v3, v45, v81
	v_add_f32_e32 v2, v41, v2
	v_exp_f32_e32 v45, v3
	v_sub_f32_e32 v3, v46, v81
	v_add_f32_e32 v2, v42, v2
	v_exp_f32_e32 v46, v3
	v_sub_f32_e32 v3, v47, v81
	v_add_f32_e32 v2, v43, v2
	v_exp_f32_e32 v47, v3
	v_sub_f32_e32 v3, v48, v81
	v_add_f32_e32 v2, v44, v2
	v_exp_f32_e32 v48, v3
	v_sub_f32_e32 v3, v49, v81
	v_add_f32_e32 v2, v45, v2
	v_exp_f32_e32 v49, v3
	v_sub_f32_e32 v3, v18, v81
	v_add_f32_e32 v2, v46, v2
	v_exp_f32_e32 v18, v3
	v_sub_f32_e32 v3, v19, v81
	v_add_f32_e32 v2, v47, v2
	v_exp_f32_e32 v19, v3
	v_sub_f32_e32 v3, v20, v81
	v_add_f32_e32 v2, v48, v2
	v_exp_f32_e32 v20, v3
	v_sub_f32_e32 v3, v21, v81
	v_add_f32_e32 v2, v49, v2
	v_exp_f32_e32 v21, v3
	v_sub_f32_e32 v3, v22, v81
	v_add_f32_e32 v2, v18, v2
	v_exp_f32_e32 v22, v3
	v_sub_f32_e32 v3, v23, v81
	v_add_f32_e32 v2, v19, v2
	v_exp_f32_e32 v23, v3
	v_sub_f32_e32 v3, v24, v81
	v_add_f32_e32 v2, v20, v2
	v_exp_f32_e32 v24, v3
	v_sub_f32_e32 v3, v25, v81
	v_add_f32_e32 v2, v21, v2
	v_exp_f32_e32 v25, v3
	v_sub_f32_e32 v3, v26, v81
	v_add_f32_e32 v2, v22, v2
	v_exp_f32_e32 v26, v3
	v_sub_f32_e32 v3, v27, v81
	v_add_f32_e32 v2, v23, v2
	v_exp_f32_e32 v27, v3
	v_sub_f32_e32 v3, v28, v81
	v_add_f32_e32 v2, v24, v2
	v_exp_f32_e32 v28, v3
	v_sub_f32_e32 v3, v29, v81
	v_add_f32_e32 v2, v25, v2
	v_exp_f32_e32 v29, v3
	v_sub_f32_e32 v3, v30, v81
	v_add_f32_e32 v2, v26, v2
	v_exp_f32_e32 v30, v3
	v_sub_f32_e32 v3, v31, v81
	v_add_f32_e32 v2, v27, v2
	v_exp_f32_e32 v31, v3
	v_sub_f32_e32 v3, v32, v81
	v_add_f32_e32 v2, v28, v2
	v_exp_f32_e32 v32, v3
	v_sub_f32_e32 v3, v33, v81
	v_add_f32_e32 v2, v29, v2
	v_exp_f32_e32 v33, v3
	v_sub_f32_e32 v3, v50, v81
	v_add_f32_e32 v2, v30, v2
	v_exp_f32_e32 v50, v3
	v_sub_f32_e32 v3, v67, v81
	v_add_f32_e32 v2, v31, v2
	v_exp_f32_e32 v242, v3
	v_sub_f32_e32 v3, v66, v81
	v_add_f32_e32 v2, v32, v2
	v_exp_f32_e32 v243, v3
	v_sub_f32_e32 v3, v68, v81
	v_add_f32_e32 v2, v33, v2
	v_exp_f32_e32 v244, v3
	v_sub_f32_e32 v3, v69, v81
	v_add_f32_e32 v2, v50, v2
	v_exp_f32_e32 v245, v3
	v_sub_f32_e32 v3, v70, v81
	v_add_f32_e32 v2, v242, v2
	v_exp_f32_e32 v246, v3
	v_sub_f32_e32 v3, v71, v81
	v_add_f32_e32 v2, v243, v2
	v_exp_f32_e32 v247, v3
	v_sub_f32_e32 v3, v72, v81
	v_add_f32_e32 v2, v244, v2
	v_exp_f32_e32 v248, v3
	v_sub_f32_e32 v3, v73, v81
	v_add_f32_e32 v2, v245, v2
	v_exp_f32_e32 v249, v3
	v_sub_f32_e32 v3, v74, v81
	v_add_f32_e32 v2, v246, v2
	v_exp_f32_e32 v250, v3
	v_sub_f32_e32 v3, v75, v81
	v_add_f32_e32 v2, v247, v2
	v_exp_f32_e32 v251, v3
	v_sub_f32_e32 v3, v76, v81
	v_add_f32_e32 v2, v248, v2
	v_exp_f32_e32 v252, v3
	v_sub_f32_e32 v3, v77, v81
	v_add_f32_e32 v2, v249, v2
	v_exp_f32_e32 v253, v3
	v_sub_f32_e32 v3, v78, v81
	v_add_f32_e32 v2, v250, v2
	v_exp_f32_e32 v219, v3
	v_sub_f32_e32 v3, v79, v81
	v_add_f32_e32 v2, v251, v2
	v_exp_f32_e32 v229, v3
	v_sub_f32_e32 v3, v80, v81
	v_add_f32_e32 v2, v252, v2
	v_exp_f32_e32 v80, v3
	v_add_f32_e32 v2, v253, v2
	v_add_f32_e32 v2, v219, v2
	v_add_f32_e32 v2, v229, v2
	v_add_f32_e32 v235, v80, v2
	ds_bpermute_b32 v236, v180, v235
	v_cvt_pk_bf16_f32 v6, v1, v51
	v_cndmask_b32_e64 v1, 0, 1, s[74:75]
	v_cvt_pk_bf16_f32 v7, v52, v53
	v_cvt_pk_bf16_f32 v8, v54, v55
	v_cvt_pk_bf16_f32 v9, v56, v57
	v_cvt_pk_bf16_f32 v2, v58, v59
	v_cvt_pk_bf16_f32 v3, v60, v61
	v_cvt_pk_bf16_f32 v4, v62, v63
	v_cvt_pk_bf16_f32 v5, v64, v65
	v_cvt_pk_bf16_f32 v76, v230, v231
	v_cvt_pk_bf16_f32 v77, v237, v238
	v_cvt_pk_bf16_f32 v78, v225, v239
	v_cvt_pk_bf16_f32 v79, v240, v241
	v_cvt_pk_bf16_f32 v72, v10, v11
	v_cvt_pk_bf16_f32 v73, v12, v13
	v_cvt_pk_bf16_f32 v74, v14, v15
	v_cvt_pk_bf16_f32 v75, v16, v17
	v_cvt_pk_bf16_f32 v68, v34, v35
	v_cvt_pk_bf16_f32 v69, v36, v37
	v_cvt_pk_bf16_f32 v70, v38, v39
	v_cvt_pk_bf16_f32 v71, v40, v41
	v_cvt_pk_bf16_f32 v64, v42, v43
	v_cvt_pk_bf16_f32 v65, v44, v45
	v_cvt_pk_bf16_f32 v66, v46, v47
	v_cvt_pk_bf16_f32 v67, v48, v49
	v_cvt_pk_bf16_f32 v60, v18, v19
	v_cvt_pk_bf16_f32 v61, v20, v21
	v_cvt_pk_bf16_f32 v62, v22, v23
	v_cvt_pk_bf16_f32 v63, v24, v25
	v_cvt_pk_bf16_f32 v56, v26, v27
	v_cvt_pk_bf16_f32 v57, v28, v29
	v_cvt_pk_bf16_f32 v58, v30, v31
	v_cvt_pk_bf16_f32 v59, v32, v33
	v_cvt_pk_bf16_f32 v52, v50, v242
	v_cvt_pk_bf16_f32 v53, v243, v244
	v_cvt_pk_bf16_f32 v54, v245, v246
	v_cvt_pk_bf16_f32 v55, v247, v248
	v_cvt_pk_bf16_f32 v48, v249, v250
	v_cvt_pk_bf16_f32 v49, v251, v252
	v_cvt_pk_bf16_f32 v50, v253, v219
	v_cvt_pk_bf16_f32 v51, v229, v80
	v_cmp_ne_u32_e64 s[72:73], 1, v1
	s_cbranch_vccnz .LBB0_203
	s_add_i32 s101, s43, 11
	v_lshlrev_b32_e32 v10, s101, v162
	s_add_i32 s100, s101, 8
	v_lshl_add_u32 v10, v164, 1, v10
	s_lshl_b32 s100, s27, s100
	s_add_i32 s74, s19, s31
	s_lshl_b32 s74, s74, 11
	s_add_i32 s74, s74, s100
	s_lshl_b32 s100, s21, 1
	s_add_i32 s74, s74, s100
	s_add_i32 s100, s101, 6
	s_lshl_b32 s100, 1, s100
	s_add_u32 s74, s94, s74
	s_addc_u32 s75, s95, 0
	global_load_dwordx4 v[114:117], v10, s[74:75]
	s_cmp_eq_u32 s27, 0
	s_cbranch_scc1 .Lv_skip01
	s_sub_u32 s74, s74, s100
	s_subb_u32 s75, s75, 0
	global_load_dwordx4 v[110:113], v10, s[74:75]
	s_sub_u32 s74, s74, s100
	s_subb_u32 s75, s75, 0
	global_load_dwordx4 v[106:109], v10, s[74:75]
	s_add_u32 s74, s74, s100
	s_addc_u32 s75, s75, 0
	s_add_u32 s74, s74, s100
	s_addc_u32 s75, s75, 0

.LBB0_498:
	v_lshlrev_b32_e32 v222, 2, v218
	v_xor_b32_e32 v236, 64, v222
	v_xor_b32_e32 v237, 0x80, v222
	s_lshl_b32 s6, s41, 2
	v_cmp_gt_u32_e64 s[4:5], 16, v218
	s_add_i32 s9, s6, 0
	s_lshl_b32 s22, s40, 10
	s_add_i32 s22, s9, s22
	v_lshl_add_u32 v224, v1, 4, s22
	v_mul_f32_e32 v244, v127, v127
	v_mul_f32_e32 v225, v129, v129
	v_fmac_f32_e32 v244, v126, v126
	v_fmac_f32_e32 v225, v128, v128
	v_add_f32_e32 v244, v244, v225
	v_mul_f32_e32 v223, v123, v123
	v_mul_f32_e32 v225, v125, v125
	v_fmac_f32_e32 v223, v122, v122
	v_fmac_f32_e32 v225, v124, v124
	v_add_f32_e32 v223, v223, v225
	v_add_f32_e32 v244, v223, v244
	v_mul_f32_e32 v223, v119, v119
	v_mul_f32_e32 v225, v121, v121
	v_fmac_f32_e32 v223, v118, v118
	v_fmac_f32_e32 v225, v120, v120
	v_add_f32_e32 v223, v223, v225
	v_add_f32_e32 v244, v223, v244
	v_mul_f32_e32 v223, v115, v115
	v_mul_f32_e32 v225, v117, v117
	v_fmac_f32_e32 v223, v114, v114
	v_fmac_f32_e32 v225, v116, v116
	v_add_f32_e32 v223, v223, v225
	v_add_f32_e32 v244, v223, v244
	v_mul_f32_e32 v245, v111, v111
	v_mul_f32_e32 v225, v113, v113
	v_fmac_f32_e32 v245, v110, v110
	v_fmac_f32_e32 v225, v112, v112
	v_add_f32_e32 v245, v245, v225
	v_mul_f32_e32 v223, v107, v107
	v_mul_f32_e32 v225, v109, v109
	v_fmac_f32_e32 v223, v106, v106
	v_fmac_f32_e32 v225, v108, v108
	v_add_f32_e32 v223, v223, v225
	v_add_f32_e32 v245, v223, v245
	v_mul_f32_e32 v223, v103, v103
	v_mul_f32_e32 v225, v105, v105
	v_fmac_f32_e32 v223, v102, v102
	v_fmac_f32_e32 v225, v104, v104
	v_add_f32_e32 v223, v223, v225
	v_add_f32_e32 v245, v223, v245
	v_mul_f32_e32 v223, v99, v99
	v_mul_f32_e32 v225, v101, v101
	v_fmac_f32_e32 v223, v98, v98
	v_fmac_f32_e32 v225, v100, v100
	v_add_f32_e32 v223, v223, v225
	v_add_f32_e32 v245, v223, v245
	v_mul_f32_e32 v246, v95, v95
	v_mul_f32_e32 v225, v97, v97
	v_fmac_f32_e32 v246, v94, v94
	v_fmac_f32_e32 v225, v96, v96
	v_add_f32_e32 v246, v246, v225
	v_mul_f32_e32 v223, v91, v91
	v_mul_f32_e32 v225, v93, v93
	v_fmac_f32_e32 v223, v90, v90
	v_fmac_f32_e32 v225, v92, v92
	v_add_f32_e32 v223, v223, v225
	v_add_f32_e32 v246, v223, v246
	v_mul_f32_e32 v223, v87, v87
	v_mul_f32_e32 v225, v89, v89
	v_fmac_f32_e32 v223, v86, v86
	v_fmac_f32_e32 v225, v88, v88
	v_add_f32_e32 v223, v223, v225
	v_add_f32_e32 v246, v223, v246
	v_mul_f32_e32 v223, v83, v83
	v_mul_f32_e32 v225, v85, v85
	v_fmac_f32_e32 v223, v82, v82
	v_fmac_f32_e32 v225, v84, v84
	v_add_f32_e32 v223, v223, v225
	v_add_f32_e32 v246, v223, v246
	v_mul_f32_e32 v247, v79, v79
	v_mul_f32_e32 v225, v81, v81
	v_fmac_f32_e32 v247, v78, v78
	v_fmac_f32_e32 v225, v80, v80
	v_add_f32_e32 v247, v247, v225
	v_mul_f32_e32 v223, v75, v75
	v_mul_f32_e32 v225, v77, v77
	v_fmac_f32_e32 v223, v74, v74
	v_fmac_f32_e32 v225, v76, v76
	v_add_f32_e32 v223, v223, v225
	v_add_f32_e32 v247, v223, v247
	v_mul_f32_e32 v223, v71, v71
	v_mul_f32_e32 v225, v73, v73
	v_fmac_f32_e32 v223, v70, v70
	v_fmac_f32_e32 v225, v72, v72
	v_add_f32_e32 v223, v223, v225
	v_add_f32_e32 v247, v223, v247
	v_mul_f32_e32 v223, v67, v67
	v_mul_f32_e32 v225, v69, v69
	v_fmac_f32_e32 v223, v66, v66
	v_fmac_f32_e32 v225, v68, v68
	v_add_f32_e32 v223, v223, v225
	v_add_f32_e32 v247, v223, v247
	v_mov_b32_e32 v248, v244
	v_mov_b32_e32 v249, v245
	v_mov_b32_e32 v250, v246
	v_mov_b32_e32 v251, v247
	v_permlane16_swap_b32_e32 v244, v248
	v_permlane16_swap_b32_e32 v245, v249
	v_permlane16_swap_b32_e32 v246, v250
	v_permlane16_swap_b32_e32 v247, v251
	v_add_f32_e32 v244, v244, v248
	v_add_f32_e32 v245, v245, v249
	v_add_f32_e32 v246, v246, v250
	v_add_f32_e32 v247, v247, v251
	v_mov_b32_e32 v248, v244
	v_mov_b32_e32 v249, v245
	v_mov_b32_e32 v250, v246
	v_mov_b32_e32 v251, v247
	v_permlane32_swap_b32_e32 v244, v248
	v_permlane32_swap_b32_e32 v245, v249
	v_permlane32_swap_b32_e32 v246, v250
	v_permlane32_swap_b32_e32 v247, v251
	s_and_saveexec_b64 s[6:7], s[4:5]
	v_add_f32_e32 v244, v244, v248
	v_add_f32_e32 v245, v245, v249
	v_add_f32_e32 v246, v246, v250
	v_add_f32_e32 v247, v247, v251
	ds_write_b32 v224, v244
	ds_write_b32 v224, v245 offset:256
	ds_write_b32 v224, v246 offset:512
	ds_write_b32 v224, v247 offset:768
	s_or_b64 exec, exec, s[6:7]
	v_mul_f32_e32 v244, v63, v63
	v_mul_f32_e32 v225, v65, v65
	v_fmac_f32_e32 v244, v62, v62
	v_fmac_f32_e32 v225, v64, v64
	v_add_f32_e32 v244, v244, v225
	v_mul_f32_e32 v223, v59, v59
	v_mul_f32_e32 v225, v61, v61
	v_fmac_f32_e32 v223, v58, v58
	v_fmac_f32_e32 v225, v60, v60
	v_add_f32_e32 v223, v223, v225
	v_add_f32_e32 v244, v223, v244
	v_mul_f32_e32 v223, v55, v55
	v_mul_f32_e32 v225, v57, v57
	v_fmac_f32_e32 v223, v54, v54
	v_fmac_f32_e32 v225, v56, v56
	v_add_f32_e32 v223, v223, v225
	v_add_f32_e32 v244, v223, v244
	v_mul_f32_e32 v223, v51, v51
	v_mul_f32_e32 v225, v53, v53
	v_fmac_f32_e32 v223, v50, v50
	v_fmac_f32_e32 v225, v52, v52
	v_add_f32_e32 v223, v223, v225
	v_add_f32_e32 v244, v223, v244
	v_mul_f32_e32 v245, v47, v47
	v_mul_f32_e32 v225, v49, v49
	v_fmac_f32_e32 v245, v46, v46
	v_fmac_f32_e32 v225, v48, v48
	v_add_f32_e32 v245, v245, v225
	v_mul_f32_e32 v223, v43, v43
	v_mul_f32_e32 v225, v45, v45
	v_fmac_f32_e32 v223, v42, v42
	v_fmac_f32_e32 v225, v44, v44
	v_add_f32_e32 v223, v223, v225
	v_add_f32_e32 v245, v223, v245
	v_mul_f32_e32 v223, v39, v39
	v_mul_f32_e32 v225, v41, v41
	v_fmac_f32_e32 v223, v38, v38
	v_fmac_f32_e32 v225, v40, v40
	v_add_f32_e32 v223, v223, v225
	v_add_f32_e32 v245, v223, v245
	v_mul_f32_e32 v223, v35, v35
	v_mul_f32_e32 v225, v37, v37
	v_fmac_f32_e32 v223, v34, v34
	v_fmac_f32_e32 v225, v36, v36
	v_add_f32_e32 v223, v223, v225
	v_add_f32_e32 v245, v223, v245
	v_mul_f32_e32 v246, v31, v31
	v_mul_f32_e32 v225, v33, v33
	v_fmac_f32_e32 v246, v30, v30
	v_fmac_f32_e32 v225, v32, v32
	v_add_f32_e32 v246, v246, v225
	v_mul_f32_e32 v223, v27, v27
	v_mul_f32_e32 v225, v29, v29
	v_fmac_f32_e32 v223, v26, v26
	v_fmac_f32_e32 v225, v28, v28
	v_add_f32_e32 v223, v223, v225
	v_add_f32_e32 v246, v223, v246
	v_mul_f32_e32 v223, v23, v23
	v_mul_f32_e32 v225, v25, v25
	v_fmac_f32_e32 v223, v22, v22
	v_fmac_f32_e32 v225, v24, v24
	v_add_f32_e32 v223, v223, v225
	v_add_f32_e32 v246, v223, v246
	v_mul_f32_e32 v223, v19, v19
	v_mul_f32_e32 v225, v21, v21
	v_fmac_f32_e32 v223, v18, v18
	v_fmac_f32_e32 v225, v20, v20
	v_add_f32_e32 v223, v223, v225
	v_add_f32_e32 v246, v223, v246
	v_mul_f32_e32 v247, v15, v15
	v_mul_f32_e32 v225, v17, v17
	v_fmac_f32_e32 v247, v14, v14
	v_fmac_f32_e32 v225, v16, v16
	v_add_f32_e32 v247, v247, v225
	v_mul_f32_e32 v223, v11, v11
	v_mul_f32_e32 v225, v13, v13
	v_fmac_f32_e32 v223, v10, v10
	v_fmac_f32_e32 v225, v12, v12
	v_add_f32_e32 v223, v223, v225
	v_add_f32_e32 v247, v223, v247
	v_mul_f32_e32 v223, v7, v7
	v_mul_f32_e32 v225, v9, v9
	v_fmac_f32_e32 v223, v6, v6
	v_fmac_f32_e32 v225, v8, v8
	v_add_f32_e32 v223, v223, v225
	v_add_f32_e32 v247, v223, v247
	v_mul_f32_e32 v223, v3, v3
	v_mul_f32_e32 v225, v5, v5
	v_fmac_f32_e32 v223, v2, v2
	v_fmac_f32_e32 v225, v4, v4
	v_add_f32_e32 v223, v223, v225
	v_add_f32_e32 v247, v223, v247
	v_mov_b32_e32 v248, v244
	v_mov_b32_e32 v249, v245
	v_mov_b32_e32 v250, v246
	v_mov_b32_e32 v251, v247
	v_permlane16_swap_b32_e32 v244, v248
	v_permlane16_swap_b32_e32 v245, v249
	v_permlane16_swap_b32_e32 v246, v250
	v_permlane16_swap_b32_e32 v247, v251
	v_add_f32_e32 v244, v244, v248
	v_add_f32_e32 v245, v245, v249
	v_add_f32_e32 v246, v246, v250
	v_add_f32_e32 v247, v247, v251
	v_mov_b32_e32 v248, v244
	v_mov_b32_e32 v249, v245
	v_mov_b32_e32 v250, v246
	v_mov_b32_e32 v251, v247
	v_permlane32_swap_b32_e32 v244, v248
	v_permlane32_swap_b32_e32 v245, v249
	v_permlane32_swap_b32_e32 v246, v250
	v_permlane32_swap_b32_e32 v247, v251
	s_and_saveexec_b64 s[6:7], s[4:5]
	v_add_f32_e32 v244, v244, v248
	v_add_f32_e32 v245, v245, v249
	v_add_f32_e32 v246, v246, v250
	v_add_f32_e32 v247, v247, v251
	ds_write_b32 v224, v244 offset:2048
	ds_write_b32 v224, v245 offset:2304
	ds_write_b32 v224, v246 offset:2560
	ds_write_b32 v224, v247 offset:2816
	s_or_b64 exec, exec, s[6:7]
	s_and_b64 s[6:7], s[16:17], exec
	s_cselect_b32 s9, 2, 3
	s_and_b64 s[6:7], s[20:21], exec
	s_cselect_b32 s9, 1, s9
	s_and_b64 s[6:7], exec, s[18:19]
	v_readlane_b32 s6, v254, 51
	s_cselect_b32 s9, 0, s9
	s_lshl_b32 s6, s6, 1
	s_add_i32 s16, s6, 6
	s_lshl_b32 s17, s9, 1
	s_and_b64 s[6:7], s[10:11], exec
	s_cselect_b32 s6, s17, s16
	s_lshl_b32 s6, s6, 18
	v_and_b32_e32 v222, 31, v233
	s_and_b32 s6, s6, 0x180000
	v_lshl_or_b32 v238, s13, 5, v222
	s_add_u32 s6, s0, s6
	v_add_u32_e32 v222, s8, v238
	s_addc_u32 s7, s1, 0
	s_waitcnt lgkmcnt(0)
	s_barrier
	s_waitcnt lgkmcnt(0)
	v_ashrrev_i32_e32 v223, 31, v222
	v_lshl_add_u64 v[222:223], v[222:223], 3, s[6:7]
	s_mov_b64 s[6:7], 0x100000
	v_lshl_add_u64 v[222:223], v[222:223], 0, s[6:7]
	v_cmp_gt_u32_e64 s[6:7], 32, v218
	s_and_saveexec_b64 s[16:17], s[6:7]
	s_cbranch_execz .LBB0_516
	v_lshl_add_u32 v224, v238, 4, 0
	ds_read_b128 v[240:243], v224
	s_mov_b32 s13, 0x3d000000
	s_waitcnt lgkmcnt(0)
	v_add_f32_e32 v224, v240, v241
	v_add_f32_e32 v225, v242, v243
	v_add_f32_e32 v224, v224, v225
	v_min_f32_e32 v224, 0x4f6e6b28, v224
	v_mul_f32_e32 v225, 0x3d000000, v224
	v_floor_f32_e32 v225, v225
	v_fma_f32 v224, v224, s13, -v225
	v_mul_f32_e32 v224, 0x4e000000, v224
	v_cvt_u32_f32_e32 v224, v224
	v_cvt_u32_f32_e32 v225, v225
	v_lshl_or_b32 v224, v224, 3, 1
	global_atomic_add_x2 v[222:223], v[224:225], off

.LBB0_600:
	s_nop 1
	s_and_b64 vcc, exec, s[14:15]
	s_cbranch_vccz .LBB0_618
	v_mul_f32_e32 v127, v127, v127
	v_mul_f32_e32 v123, v123, v123
	v_fmac_f32_e32 v127, v126, v126
	v_mul_f32_e32 v126, v129, v129
	v_fmac_f32_e32 v123, v122, v122
	v_mul_f32_e32 v122, v125, v125
	v_mul_f32_e32 v119, v119, v119
	v_fmac_f32_e32 v126, v128, v128
	v_fmac_f32_e32 v122, v124, v124
	v_fmac_f32_e32 v119, v118, v118
	v_mul_f32_e32 v118, v121, v121
	v_mul_f32_e32 v115, v115, v115
	v_add_f32_e32 v126, v127, v126
	v_add_f32_e32 v122, v123, v122
	v_fmac_f32_e32 v118, v120, v120
	v_fmac_f32_e32 v115, v114, v114
	v_mul_f32_e32 v114, v117, v117
	v_add_f32_e32 v122, v126, v122
	v_add_f32_e32 v118, v119, v118
	v_fmac_f32_e32 v114, v116, v116
	v_add_f32_e32 v118, v118, v122
	v_add_f32_e32 v114, v115, v114
	v_add_f32_e32 v114, v114, v118
	v_mov_b32_e32 v115, v114
	s_lshl_b32 s6, s9, 16
	s_add_u32 s6, s78, s6
	s_addc_u32 s7, s79, 0
	s_add_u32 s9, s6, 0x10000
	v_permlane16_swap_b32_e32 v114, v115
	v_add_f32_e32 v114, v114, v115
	s_addc_u32 s13, s7, 0
	v_mov_b32_e32 v115, v114
	s_and_b64 s[6:7], s[10:11], exec
	v_readlane_b32 s6, v254, 54
	v_readlane_b32 s7, v254, 55
	s_cselect_b32 s10, s13, s7
	s_cselect_b32 s11, s9, s6
	v_permlane32_swap_b32_e32 v114, v115
	s_ashr_i32 s9, s8, 31
	s_ashr_i32 s13, s12, 31
	v_lshlrev_b32_e32 v1, 2, v1
	s_and_saveexec_b64 s[6:7], s[4:5]
	s_mov_b32 s18, 0x45800000
	s_cbranch_execz .LBB0_603
	s_waitcnt lgkmcnt(0)
	v_add_f32_e32 v114, v114, v115
	v_min_f32_e32 v114, 0x49742400, v114
	s_lshl_b64 s[14:15], s[8:9], 2
	v_fma_f32 v114, v114, s18, 0.5
	s_add_u32 s16, s11, s14
	v_cvt_u32_f32_e32 v114, v114
	s_addc_u32 s17, s10, s15
	s_lshl_b64 s[14:15], s[12:13], 2
	s_add_u32 s14, s16, s14
	s_addc_u32 s15, s17, s15
	global_atomic_add v1, v114, s[14:15]
.LBB0_603:
	s_or_b64 exec, exec, s[6:7]
	v_mul_f32_e32 v111, v111, v111
	v_mul_f32_e32 v107, v107, v107
	v_fmac_f32_e32 v111, v110, v110
	v_mul_f32_e32 v110, v113, v113
	v_fmac_f32_e32 v107, v106, v106
	v_mul_f32_e32 v106, v109, v109
	v_mul_f32_e32 v103, v103, v103
	v_fmac_f32_e32 v110, v112, v112
	v_fmac_f32_e32 v106, v108, v108
	v_fmac_f32_e32 v103, v102, v102
	v_mul_f32_e32 v102, v105, v105
	v_mul_f32_e32 v99, v99, v99
	v_add_f32_e32 v110, v111, v110
	v_add_f32_e32 v106, v107, v106
	v_fmac_f32_e32 v102, v104, v104
	v_fmac_f32_e32 v99, v98, v98
	v_mul_f32_e32 v98, v101, v101
	v_add_f32_e32 v106, v110, v106
	v_add_f32_e32 v102, v103, v102
	v_fmac_f32_e32 v98, v100, v100
	v_add_f32_e32 v102, v102, v106
	v_add_f32_e32 v98, v99, v98
	v_add_f32_e32 v98, v98, v102
	v_mul_f32_e32 v95, v95, v95
	v_mul_f32_e32 v91, v91, v91
	v_fmac_f32_e32 v95, v94, v94
	v_mul_f32_e32 v94, v97, v97
	v_fmac_f32_e32 v91, v90, v90
	v_mul_f32_e32 v90, v93, v93
	v_mul_f32_e32 v87, v87, v87
	v_fmac_f32_e32 v94, v96, v96
	v_fmac_f32_e32 v90, v92, v92
	v_fmac_f32_e32 v87, v86, v86
	v_mul_f32_e32 v86, v89, v89
	v_mul_f32_e32 v83, v83, v83
	v_add_f32_e32 v94, v95, v94
	v_add_f32_e32 v90, v91, v90
	v_fmac_f32_e32 v86, v88, v88
	v_fmac_f32_e32 v83, v82, v82
	v_mul_f32_e32 v82, v85, v85
	v_add_f32_e32 v90, v94, v90
	v_add_f32_e32 v86, v87, v86
	v_fmac_f32_e32 v82, v84, v84
	v_add_f32_e32 v86, v86, v90
	v_add_f32_e32 v82, v83, v82
	v_add_f32_e32 v82, v82, v86
	v_mul_f32_e32 v79, v79, v79
	v_mul_f32_e32 v75, v75, v75
	v_fmac_f32_e32 v79, v78, v78
	v_mul_f32_e32 v78, v81, v81
	v_fmac_f32_e32 v75, v74, v74
	v_mul_f32_e32 v74, v77, v77
	v_mul_f32_e32 v71, v71, v71
	v_fmac_f32_e32 v78, v80, v80
	v_fmac_f32_e32 v74, v76, v76
	v_fmac_f32_e32 v71, v70, v70
	v_mul_f32_e32 v70, v73, v73
	v_mul_f32_e32 v67, v67, v67
	v_add_f32_e32 v78, v79, v78
	v_add_f32_e32 v74, v75, v74
	v_fmac_f32_e32 v70, v72, v72
	v_fmac_f32_e32 v67, v66, v66
	v_mul_f32_e32 v66, v69, v69
	v_add_f32_e32 v74, v78, v74
	v_add_f32_e32 v70, v71, v70
	v_fmac_f32_e32 v66, v68, v68
	v_add_f32_e32 v70, v70, v74
	v_add_f32_e32 v66, v67, v66
	v_add_f32_e32 v66, v66, v70
	v_mul_f32_e32 v63, v63, v63
	v_mul_f32_e32 v59, v59, v59
	v_fmac_f32_e32 v63, v62, v62
	v_mul_f32_e32 v62, v65, v65
	v_fmac_f32_e32 v59, v58, v58
	v_mul_f32_e32 v58, v61, v61
	v_mul_f32_e32 v55, v55, v55
	v_fmac_f32_e32 v62, v64, v64
	v_fmac_f32_e32 v58, v60, v60
	v_fmac_f32_e32 v55, v54, v54
	v_mul_f32_e32 v54, v57, v57
	v_mul_f32_e32 v51, v51, v51
	v_add_f32_e32 v62, v63, v62
	v_add_f32_e32 v58, v59, v58
	v_fmac_f32_e32 v54, v56, v56
	v_fmac_f32_e32 v51, v50, v50
	v_mul_f32_e32 v50, v53, v53
	v_add_f32_e32 v58, v62, v58
	v_add_f32_e32 v54, v55, v54
	v_fmac_f32_e32 v50, v52, v52
	v_add_f32_e32 v54, v54, v58
	v_add_f32_e32 v50, v51, v50
	v_add_f32_e32 v50, v50, v54
	v_mul_f32_e32 v47, v47, v47
	v_mul_f32_e32 v43, v43, v43
	v_fmac_f32_e32 v47, v46, v46
	v_mul_f32_e32 v46, v49, v49
	v_fmac_f32_e32 v43, v42, v42
	v_mul_f32_e32 v42, v45, v45
	v_mul_f32_e32 v39, v39, v39
	v_fmac_f32_e32 v46, v48, v48
	v_fmac_f32_e32 v42, v44, v44
	v_fmac_f32_e32 v39, v38, v38
	v_mul_f32_e32 v38, v41, v41
	v_mul_f32_e32 v35, v35, v35
	v_add_f32_e32 v46, v47, v46
	v_add_f32_e32 v42, v43, v42
	v_fmac_f32_e32 v38, v40, v40
	v_fmac_f32_e32 v35, v34, v34
	v_mul_f32_e32 v34, v37, v37
	v_add_f32_e32 v42, v46, v42
	v_add_f32_e32 v38, v39, v38
	v_fmac_f32_e32 v34, v36, v36
	v_add_f32_e32 v38, v38, v42
	v_add_f32_e32 v34, v35, v34
	v_add_f32_e32 v34, v34, v38
	v_mul_f32_e32 v31, v31, v31
	v_mul_f32_e32 v27, v27, v27
	v_fmac_f32_e32 v31, v30, v30
	v_mul_f32_e32 v30, v33, v33
	v_fmac_f32_e32 v27, v26, v26
	v_mul_f32_e32 v26, v29, v29
	v_mul_f32_e32 v23, v23, v23
	v_fmac_f32_e32 v30, v32, v32
	v_fmac_f32_e32 v26, v28, v28
	v_fmac_f32_e32 v23, v22, v22
	v_mul_f32_e32 v22, v25, v25
	v_mul_f32_e32 v19, v19, v19
	v_add_f32_e32 v30, v31, v30
	v_add_f32_e32 v26, v27, v26
	v_fmac_f32_e32 v22, v24, v24
	v_fmac_f32_e32 v19, v18, v18
	v_mul_f32_e32 v18, v21, v21
	v_add_f32_e32 v26, v30, v26
	v_add_f32_e32 v22, v23, v22
	v_fmac_f32_e32 v18, v20, v20
	v_add_f32_e32 v22, v22, v26
	v_add_f32_e32 v18, v19, v18
	v_add_f32_e32 v18, v18, v22
	v_mul_f32_e32 v15, v15, v15
	v_mul_f32_e32 v11, v11, v11
	v_fmac_f32_e32 v15, v14, v14
	v_mul_f32_e32 v14, v17, v17
	v_fmac_f32_e32 v11, v10, v10
	v_mul_f32_e32 v10, v13, v13
	v_mul_f32_e32 v7, v7, v7
	v_fmac_f32_e32 v14, v16, v16
	v_fmac_f32_e32 v10, v12, v12
	v_fmac_f32_e32 v7, v6, v6
	v_mul_f32_e32 v6, v9, v9
	v_mul_f32_e32 v3, v3, v3
	v_add_f32_e32 v14, v15, v14
	v_add_f32_e32 v10, v11, v10
	v_fmac_f32_e32 v6, v8, v8
	v_fmac_f32_e32 v3, v2, v2
	v_mul_f32_e32 v2, v5, v5
	v_add_f32_e32 v10, v14, v10
	v_add_f32_e32 v6, v7, v6
	v_fmac_f32_e32 v2, v4, v4
	v_add_f32_e32 v6, v6, v10
	v_add_f32_e32 v2, v3, v2
	v_add_f32_e32 v2, v2, v6
	v_mov_b32_e32 v99, v98
	v_mov_b32_e32 v83, v82
	v_mov_b32_e32 v67, v66
	v_mov_b32_e32 v51, v50
	v_mov_b32_e32 v35, v34
	v_mov_b32_e32 v19, v18
	v_mov_b32_e32 v3, v2
	v_permlane16_swap_b32_e32 v98, v99
	v_permlane16_swap_b32_e32 v82, v83
	v_permlane16_swap_b32_e32 v66, v67
	v_permlane16_swap_b32_e32 v50, v51
	v_permlane16_swap_b32_e32 v34, v35
	v_permlane16_swap_b32_e32 v18, v19
	v_permlane16_swap_b32_e32 v2, v3
	v_add_f32_e32 v98, v98, v99
	v_add_f32_e32 v82, v82, v83
	v_add_f32_e32 v66, v66, v67
	v_add_f32_e32 v50, v50, v51
	v_add_f32_e32 v34, v34, v35
	v_add_f32_e32 v18, v18, v19
	v_add_f32_e32 v2, v2, v3
	v_mov_b32_e32 v99, v98
	v_mov_b32_e32 v83, v82
	v_mov_b32_e32 v67, v66
	v_mov_b32_e32 v51, v50
	v_mov_b32_e32 v35, v34
	v_mov_b32_e32 v19, v18
	v_mov_b32_e32 v3, v2
	v_permlane32_swap_b32_e32 v98, v99
	v_permlane32_swap_b32_e32 v82, v83
	v_permlane32_swap_b32_e32 v66, v67
	v_permlane32_swap_b32_e32 v50, v51
	v_permlane32_swap_b32_e32 v34, v35
	v_permlane32_swap_b32_e32 v18, v19
	v_permlane32_swap_b32_e32 v2, v3
	s_and_saveexec_b64 s[6:7], s[4:5]
	v_add_f32_e32 v98, v98, v99
	v_min_f32_e32 v98, 0x49742400, v98
	v_fma_f32 v98, v98, s18, 0.5
	v_cvt_u32_f32_e32 v98, v98
	v_add_f32_e32 v82, v82, v83
	v_min_f32_e32 v82, 0x49742400, v82
	v_fma_f32 v82, v82, s18, 0.5
	v_cvt_u32_f32_e32 v82, v82
	v_add_f32_e32 v66, v66, v67
	v_min_f32_e32 v66, 0x49742400, v66
	v_fma_f32 v66, v66, s18, 0.5
	v_cvt_u32_f32_e32 v66, v66
	v_add_f32_e32 v50, v50, v51
	v_min_f32_e32 v50, 0x49742400, v50
	v_fma_f32 v50, v50, s18, 0.5
	v_cvt_u32_f32_e32 v50, v50
	v_add_f32_e32 v34, v34, v35
	v_min_f32_e32 v34, 0x49742400, v34
	v_fma_f32 v34, v34, s18, 0.5
	v_cvt_u32_f32_e32 v34, v34
	v_add_f32_e32 v18, v18, v19
	v_min_f32_e32 v18, 0x49742400, v18
	v_fma_f32 v18, v18, s18, 0.5
	v_cvt_u32_f32_e32 v18, v18
	v_add_f32_e32 v2, v2, v3
	v_min_f32_e32 v2, 0x49742400, v2
	v_fma_f32 v2, v2, s18, 0.5
	v_cvt_u32_f32_e32 v2, v2
	s_lshl_b64 s[14:15], s[8:9], 2
	s_add_u32 s16, s11, s14
	s_addc_u32 s17, s10, s15
	s_lshl_b64 s[14:15], s[12:13], 2
	s_add_u32 s14, s16, s14
	s_addc_u32 s15, s17, s15
	global_atomic_add v1, v98, s[14:15] offset:64
	global_atomic_add v1, v82, s[14:15] offset:128
	global_atomic_add v1, v66, s[14:15] offset:192
	global_atomic_add v1, v50, s[14:15] offset:512
	global_atomic_add v1, v34, s[14:15] offset:576
	global_atomic_add v1, v18, s[14:15] offset:640
	s_lshl_b64 s[4:5], s[8:9], 2
	s_add_u32 s8, s11, s4
	s_addc_u32 s9, s10, s5
	s_lshl_b64 s[4:5], s[12:13], 2
	s_add_u32 s4, s8, s4
	s_addc_u32 s5, s9, s5
	global_atomic_add v1, v2, s[4:5] offset:704
	s_or_b64 exec, exec, s[6:7]
